# split-K sample-row reductions (branch/out/down, 5 of 6): every arriving workgroup waits for all slabs and sums rows a, a+nsplit.. instead of the last arriver summing all 16 row-steps alone
# speedup vs baseline: 1.0153x; 1.0077x over previous
.LBB0_585:
	s_and_b64 vcc, exec, s[26:27]
	s_cbranch_vccz .LBB0_591
	v_lshl_add_u64 v[66:67], v[162:163], 0, v[174:175]
	global_load_dwordx2 v[68:69], v[66:67], off
	s_add_i32 s8, s8, s56
	s_lshl_b64 s[26:27], s[8:9], 20
	s_add_u32 vcc_lo, s4, s26
	s_addc_u32 vcc_hi, s5, s27
	v_lshl_add_u64 v[70:71], vcc, 0, v[154:155]
	v_lshlrev_b64 v[64:65], 2, v[174:175]
	v_lshl_add_u64 v[70:71], v[70:71], 0, v[64:65]
	s_waitcnt vmcnt(0)
	v_cvt_f32_ubyte3_e32 v73, v68
	v_cvt_f32_ubyte2_e32 v72, v68
	v_cvt_f32_ubyte1_e32 v75, v68
	v_cvt_f32_ubyte0_e32 v74, v68
	v_pk_mul_f32 v[74:75], v[74:75], s[74:75] op_sel_hi:[1,0]
	v_pk_mul_f32 v[72:73], v[72:73], s[74:75] op_sel_hi:[1,0]
	v_pk_mul_f32 v[60:61], v[60:61], v[74:75]
	v_pk_mul_f32 v[62:63], v[62:63], v[72:73]
	global_store_dwordx4 v[70:71], v[60:63], off
	s_nop 1
	v_cvt_f32_ubyte3_e32 v61, v69
	v_cvt_f32_ubyte2_e32 v60, v69
	v_cvt_f32_ubyte1_e32 v63, v69
	v_cvt_f32_ubyte0_e32 v62, v69
	v_pk_mul_f32 v[62:63], v[62:63], s[74:75] op_sel_hi:[1,0]
	v_pk_mul_f32 v[60:61], v[60:61], s[74:75] op_sel_hi:[1,0]
	v_pk_mul_f32 v[56:57], v[56:57], v[62:63]
	v_pk_mul_f32 v[58:59], v[58:59], v[60:61]
	global_store_dwordx4 v[70:71], v[56:59], off offset:16
	global_load_dwordx2 v[56:57], v[66:67], off offset:128
	s_waitcnt vmcnt(0)
	v_cvt_f32_ubyte1_e32 v61, v56
	v_cvt_f32_ubyte3_e32 v59, v56
	v_cvt_f32_ubyte2_e32 v58, v56
	v_cvt_f32_ubyte0_e32 v60, v56
	v_pk_mul_f32 v[60:61], v[60:61], s[74:75] op_sel_hi:[1,0]
	v_pk_mul_f32 v[58:59], v[58:59], s[74:75] op_sel_hi:[1,0]
	v_pk_mul_f32 v[52:53], v[52:53], v[60:61]
	v_pk_mul_f32 v[54:55], v[54:55], v[58:59]
	global_store_dwordx4 v[70:71], v[52:55], off offset:512
	s_nop 1
	v_cvt_f32_ubyte3_e32 v53, v57
	v_cvt_f32_ubyte2_e32 v52, v57
	v_cvt_f32_ubyte1_e32 v55, v57
	v_cvt_f32_ubyte0_e32 v54, v57
	v_pk_mul_f32 v[54:55], v[54:55], s[74:75] op_sel_hi:[1,0]
	v_pk_mul_f32 v[52:53], v[52:53], s[74:75] op_sel_hi:[1,0]
	v_pk_mul_f32 v[48:49], v[48:49], v[54:55]
	v_pk_mul_f32 v[50:51], v[50:51], v[52:53]
	global_store_dwordx4 v[70:71], v[48:51], off offset:528
	v_lshl_add_u64 v[52:53], vcc, 0, v[156:157]
	v_lshl_add_u64 v[52:53], v[52:53], 0, v[64:65]
	v_lshl_add_u64 v[48:49], v[164:165], 0, v[174:175]
	global_load_dwordx2 v[50:51], v[48:49], off
	s_waitcnt vmcnt(0)
	v_cvt_f32_ubyte3_e32 v55, v50
	v_cvt_f32_ubyte2_e32 v54, v50
	v_cvt_f32_ubyte1_e32 v57, v50
	v_cvt_f32_ubyte0_e32 v56, v50
	v_pk_mul_f32 v[56:57], v[56:57], s[74:75] op_sel_hi:[1,0]
	v_pk_mul_f32 v[54:55], v[54:55], s[74:75] op_sel_hi:[1,0]
	v_pk_mul_f32 v[44:45], v[44:45], v[56:57]
	v_pk_mul_f32 v[46:47], v[46:47], v[54:55]
	global_store_dwordx4 v[52:53], v[44:47], off
	s_nop 1
	v_cvt_f32_ubyte3_e32 v45, v51
	v_cvt_f32_ubyte2_e32 v44, v51
	v_cvt_f32_ubyte1_e32 v47, v51
	v_cvt_f32_ubyte0_e32 v46, v51
	v_pk_mul_f32 v[46:47], v[46:47], s[74:75] op_sel_hi:[1,0]
	v_pk_mul_f32 v[44:45], v[44:45], s[74:75] op_sel_hi:[1,0]
	v_pk_mul_f32 v[40:41], v[40:41], v[46:47]
	v_pk_mul_f32 v[42:43], v[42:43], v[44:45]
	global_store_dwordx4 v[52:53], v[40:43], off offset:16
	global_load_dwordx2 v[40:41], v[48:49], off offset:128
	s_waitcnt vmcnt(0)
	v_cvt_f32_ubyte1_e32 v45, v40
	v_cvt_f32_ubyte3_e32 v43, v40
	v_cvt_f32_ubyte2_e32 v42, v40
	v_cvt_f32_ubyte0_e32 v44, v40
	v_pk_mul_f32 v[44:45], v[44:45], s[74:75] op_sel_hi:[1,0]
	v_pk_mul_f32 v[42:43], v[42:43], s[74:75] op_sel_hi:[1,0]
	v_pk_mul_f32 v[36:37], v[36:37], v[44:45]
	v_pk_mul_f32 v[38:39], v[38:39], v[42:43]
	global_store_dwordx4 v[52:53], v[36:39], off offset:512
	s_nop 1
	v_cvt_f32_ubyte3_e32 v37, v41
	v_cvt_f32_ubyte2_e32 v36, v41
	v_cvt_f32_ubyte1_e32 v39, v41
	v_cvt_f32_ubyte0_e32 v38, v41
	v_pk_mul_f32 v[38:39], v[38:39], s[74:75] op_sel_hi:[1,0]
	v_pk_mul_f32 v[36:37], v[36:37], s[74:75] op_sel_hi:[1,0]
	v_pk_mul_f32 v[32:33], v[32:33], v[38:39]
	v_pk_mul_f32 v[34:35], v[34:35], v[36:37]
	global_store_dwordx4 v[52:53], v[32:35], off offset:528
	v_lshl_add_u64 v[36:37], vcc, 0, v[158:159]
	v_lshl_add_u64 v[36:37], v[36:37], 0, v[64:65]
	v_lshl_add_u64 v[32:33], v[166:167], 0, v[174:175]
	global_load_dwordx2 v[34:35], v[32:33], off
	s_waitcnt vmcnt(0)
	v_cvt_f32_ubyte3_e32 v39, v34
	v_cvt_f32_ubyte2_e32 v38, v34
	v_cvt_f32_ubyte1_e32 v41, v34
	v_cvt_f32_ubyte0_e32 v40, v34
	v_pk_mul_f32 v[40:41], v[40:41], s[74:75] op_sel_hi:[1,0]
	v_pk_mul_f32 v[38:39], v[38:39], s[74:75] op_sel_hi:[1,0]
	v_pk_mul_f32 v[28:29], v[28:29], v[40:41]
	v_pk_mul_f32 v[30:31], v[30:31], v[38:39]
	global_store_dwordx4 v[36:37], v[28:31], off
	s_nop 1
	v_cvt_f32_ubyte3_e32 v29, v35
	v_cvt_f32_ubyte2_e32 v28, v35
	v_cvt_f32_ubyte1_e32 v31, v35
	v_cvt_f32_ubyte0_e32 v30, v35
	v_pk_mul_f32 v[30:31], v[30:31], s[74:75] op_sel_hi:[1,0]
	v_pk_mul_f32 v[28:29], v[28:29], s[74:75] op_sel_hi:[1,0]
	v_pk_mul_f32 v[24:25], v[24:25], v[30:31]
	v_pk_mul_f32 v[26:27], v[26:27], v[28:29]
	global_store_dwordx4 v[36:37], v[24:27], off offset:16
	global_load_dwordx2 v[24:25], v[32:33], off offset:128
	s_waitcnt vmcnt(0)
	v_cvt_f32_ubyte1_e32 v29, v24
	v_cvt_f32_ubyte3_e32 v27, v24
	v_cvt_f32_ubyte2_e32 v26, v24
	v_cvt_f32_ubyte0_e32 v28, v24
	v_pk_mul_f32 v[28:29], v[28:29], s[74:75] op_sel_hi:[1,0]
	v_pk_mul_f32 v[26:27], v[26:27], s[74:75] op_sel_hi:[1,0]
	v_pk_mul_f32 v[20:21], v[20:21], v[28:29]
	v_pk_mul_f32 v[22:23], v[22:23], v[26:27]
	global_store_dwordx4 v[36:37], v[20:23], off offset:512
	s_nop 1
	v_cvt_f32_ubyte3_e32 v21, v25
	v_cvt_f32_ubyte2_e32 v20, v25
	v_cvt_f32_ubyte1_e32 v23, v25
	v_cvt_f32_ubyte0_e32 v22, v25
	v_pk_mul_f32 v[22:23], v[22:23], s[74:75] op_sel_hi:[1,0]
	v_pk_mul_f32 v[20:21], v[20:21], s[74:75] op_sel_hi:[1,0]
	v_pk_mul_f32 v[16:17], v[16:17], v[22:23]
	v_pk_mul_f32 v[18:19], v[18:19], v[20:21]
	global_store_dwordx4 v[36:37], v[16:19], off offset:528
	v_lshl_add_u64 v[20:21], vcc, 0, v[160:161]
	v_lshl_add_u64 v[20:21], v[20:21], 0, v[64:65]
	v_lshl_add_u64 v[16:17], v[168:169], 0, v[174:175]
	global_load_dwordx2 v[18:19], v[16:17], off
	s_waitcnt vmcnt(0)
	v_cvt_f32_ubyte3_e32 v23, v18
	v_cvt_f32_ubyte2_e32 v22, v18
	v_cvt_f32_ubyte1_e32 v25, v18
	v_cvt_f32_ubyte0_e32 v24, v18
	v_pk_mul_f32 v[24:25], v[24:25], s[74:75] op_sel_hi:[1,0]
	v_pk_mul_f32 v[22:23], v[22:23], s[74:75] op_sel_hi:[1,0]
	v_pk_mul_f32 v[12:13], v[12:13], v[24:25]
	v_pk_mul_f32 v[14:15], v[14:15], v[22:23]
	global_store_dwordx4 v[20:21], v[12:15], off
	s_nop 1
	v_cvt_f32_ubyte3_e32 v13, v19
	v_cvt_f32_ubyte2_e32 v12, v19
	v_cvt_f32_ubyte1_e32 v15, v19
	v_cvt_f32_ubyte0_e32 v14, v19
	v_pk_mul_f32 v[14:15], v[14:15], s[74:75] op_sel_hi:[1,0]
	v_pk_mul_f32 v[12:13], v[12:13], s[74:75] op_sel_hi:[1,0]
	v_pk_mul_f32 v[8:9], v[8:9], v[14:15]
	v_pk_mul_f32 v[10:11], v[10:11], v[12:13]
	global_store_dwordx4 v[20:21], v[8:11], off offset:16
	global_load_dwordx2 v[8:9], v[16:17], off offset:128
	s_waitcnt vmcnt(0)
	v_cvt_f32_ubyte1_e32 v13, v8
	v_cvt_f32_ubyte3_e32 v11, v8
	v_cvt_f32_ubyte2_e32 v10, v8
	v_cvt_f32_ubyte0_e32 v12, v8
	v_pk_mul_f32 v[12:13], v[12:13], s[74:75] op_sel_hi:[1,0]
	v_pk_mul_f32 v[10:11], v[10:11], s[74:75] op_sel_hi:[1,0]
	v_pk_mul_f32 v[4:5], v[4:5], v[12:13]
	v_pk_mul_f32 v[6:7], v[6:7], v[10:11]
	global_store_dwordx4 v[20:21], v[4:7], off offset:512
	s_nop 1
	v_cvt_f32_ubyte3_e32 v5, v9
	v_cvt_f32_ubyte2_e32 v4, v9
	v_cvt_f32_ubyte1_e32 v7, v9
	v_cvt_f32_ubyte0_e32 v6, v9
	v_pk_mul_f32 v[6:7], v[6:7], s[74:75] op_sel_hi:[1,0]
	v_pk_mul_f32 v[4:5], v[4:5], s[74:75] op_sel_hi:[1,0]
	v_pk_mul_f32 v[0:1], v[0:1], v[6:7]
	v_pk_mul_f32 v[2:3], v[2:3], v[4:5]
	global_store_dwordx4 v[20:21], v[0:3], off offset:528
	s_waitcnt vmcnt(0)
	s_barrier
	s_and_saveexec_b64 s[26:27], s[18:19]
	s_cbranch_execz .LBB0_588
	s_lshl_b32 s34, s10, 6
	s_ashr_i32 s35, s34, 31
	s_lshl_b64 s[34:35], s[34:35], 2
	s_add_u32 s34, s75, s34
	s_addc_u32 s35, s21, s35
	buffer_wbl2 sc1
	s_waitcnt vmcnt(0)
	s_waitcnt vmcnt(0)
	v_mov_b64_e32 v[0:1], s[34:35]
	flat_atomic_add v0, v[0:1], v182 sc0
	s_waitcnt vmcnt(0) lgkmcnt(0)
	ds_write_b32 v145, v0
	v_mov_b64_e32 v[2:3], s[34:35]
.Lsl_spin_br1:
	global_load_dword v4, v[2:3], off sc1
	s_waitcnt vmcnt(0)
	v_cmp_gt_u32_e32 vcc, 12, v4
	s_cbranch_vccz .Lsl_go_br1
	s_sleep 1
	s_branch .Lsl_spin_br1
.Lsl_go_br1:
.LBB0_588:
	s_or_b64 exec, exec, s[26:27]
	s_waitcnt lgkmcnt(0)
	s_barrier
	ds_read_b32 v0, v145
	s_waitcnt lgkmcnt(0)
	v_readfirstlane_b32 s8, v0
	v_mov_b32_e32 v52, v183
	s_waitcnt vmcnt(0)
	buffer_inv sc1
	s_waitcnt vmcnt(0)
	s_lshl_b32 s8, s8, 9
	v_lshlrev_b32_e32 v0, 2, v52
	v_and_b32_e32 v0, 0xfc, v0
	v_or_b32_e32 v0, s28, v0
	v_ashrrev_i32_e32 v1, 31, v0
	v_lshl_add_u64 v[44:45], v[0:1], 2, s[4:5]
	v_lshl_add_u64 v[46:47], v[0:1], 1, s[2:3]
	s_cmpk_lt_i32 s8, 0x2000
	s_cbranch_scc0 .LBB0_591
.LBB0_590:
	v_add_u32_e32 v53, s8, v52
	v_ashrrev_i32_e32 v54, 6, v53
	v_ashrrev_i32_e32 v55, 31, v54
	v_lshlrev_b64 v[0:1], 13, v[54:55]
	v_lshl_add_u64 v[48:49], v[44:45], 0, v[0:1]
	v_add_co_u32_e32 v4, vcc, 0x100000, v48
	global_load_dwordx4 v[0:3], v[48:49], off
	s_nop 0
	v_addc_co_u32_e32 v5, vcc, 0, v49, vcc
	v_add_co_u32_e32 v8, vcc, 0x200000, v48
	global_load_dwordx4 v[4:7], v[4:5], off
	s_nop 0
	v_addc_co_u32_e32 v9, vcc, 0, v49, vcc
	v_add_co_u32_e32 v12, vcc, 0x300000, v48
	global_load_dwordx4 v[8:11], v[8:9], off
	s_nop 0
	v_addc_co_u32_e32 v13, vcc, 0, v49, vcc
	v_add_co_u32_e32 v16, vcc, 0x400000, v48
	global_load_dwordx4 v[12:15], v[12:13], off
	s_nop 0
	v_addc_co_u32_e32 v17, vcc, 0, v49, vcc
	v_add_co_u32_e32 v20, vcc, 0x500000, v48
	global_load_dwordx4 v[16:19], v[16:17], off
	s_nop 0
	v_addc_co_u32_e32 v21, vcc, 0, v49, vcc
	v_add_co_u32_e32 v24, vcc, 0x600000, v48
	global_load_dwordx4 v[20:23], v[20:21], off
	s_nop 0
	v_addc_co_u32_e32 v25, vcc, 0, v49, vcc
	v_add_co_u32_e32 v28, vcc, 0x700000, v48
	global_load_dwordx4 v[24:27], v[24:25], off
	s_nop 0
	v_addc_co_u32_e32 v29, vcc, 0, v49, vcc
	v_add_co_u32_e32 v32, vcc, 0x800000, v48
	global_load_dwordx4 v[28:31], v[28:29], off
	s_nop 0
	v_addc_co_u32_e32 v33, vcc, 0, v49, vcc
	v_add_co_u32_e32 v36, vcc, 0x900000, v48
	global_load_dwordx4 v[32:35], v[32:33], off
	s_nop 0
	v_addc_co_u32_e32 v37, vcc, 0, v49, vcc
	v_add_co_u32_e32 v40, vcc, 0xa00000, v48
	global_load_dwordx4 v[36:39], v[36:37], off
	s_nop 0
	v_addc_co_u32_e32 v41, vcc, 0, v49, vcc
	v_add_co_u32_e32 v48, vcc, 0xb00000, v48
	global_load_dwordx4 v[40:43], v[40:41], off
	s_nop 0
	v_addc_co_u32_e32 v49, vcc, 0, v49, vcc
	global_load_dwordx4 v[48:51], v[48:49], off
	s_brev_b32 s10, 64
	s_addk_i32 s8, 0x400
	s_cmpk_eq_i32 s8, 0x2000
	s_waitcnt vmcnt(11)
	v_pk_add_f32 v[2:3], v[2:3], 0 op_sel_hi:[1,0]
	v_pk_add_f32 v[0:1], v[0:1], 0 op_sel_hi:[1,0]
	s_waitcnt vmcnt(10)
	v_pk_add_f32 v[2:3], v[2:3], v[6:7]
	v_pk_add_f32 v[0:1], v[0:1], v[4:5]
	s_waitcnt vmcnt(9)
	v_pk_add_f32 v[2:3], v[2:3], v[10:11]
	v_pk_add_f32 v[0:1], v[0:1], v[8:9]
	s_waitcnt vmcnt(8)
	v_pk_add_f32 v[2:3], v[2:3], v[14:15]
	v_pk_add_f32 v[0:1], v[0:1], v[12:13]
	s_waitcnt vmcnt(7)
	v_pk_add_f32 v[2:3], v[2:3], v[18:19]
	v_pk_add_f32 v[0:1], v[0:1], v[16:17]
	s_waitcnt vmcnt(6)
	v_pk_add_f32 v[2:3], v[2:3], v[22:23]
	v_pk_add_f32 v[0:1], v[0:1], v[20:21]
	s_waitcnt vmcnt(5)
	v_pk_add_f32 v[2:3], v[2:3], v[26:27]
	v_pk_add_f32 v[0:1], v[0:1], v[24:25]
	s_waitcnt vmcnt(4)
	v_pk_add_f32 v[2:3], v[2:3], v[30:31]
	v_pk_add_f32 v[0:1], v[0:1], v[28:29]
	s_waitcnt vmcnt(3)
	v_pk_add_f32 v[2:3], v[2:3], v[34:35]
	v_pk_add_f32 v[0:1], v[0:1], v[32:33]
	s_waitcnt vmcnt(2)
	v_pk_add_f32 v[2:3], v[2:3], v[38:39]
	v_pk_add_f32 v[0:1], v[0:1], v[36:37]
	s_waitcnt vmcnt(1)
	v_pk_add_f32 v[2:3], v[2:3], v[42:43]
	v_pk_add_f32 v[0:1], v[0:1], v[40:41]
	s_waitcnt vmcnt(0)
	v_pk_add_f32 v[2:3], v[2:3], v[50:51]
	v_pk_add_f32 v[0:1], v[0:1], v[48:49]
	s_nop 0
	s_nop 1
	v_cvt_pk_bf16_f32 v0, v0, v1
	s_nop 1
	v_cvt_pk_bf16_f32 v1, v2, v3
	v_lshlrev_b64 v[2:3], 12, v[54:55]
	v_lshl_add_u64 v[2:3], v[46:47], 0, v[2:3]
	v_add_co_u32_e32 v2, vcc, s10, v2
	s_mov_b32 s10, 0x100000
	s_nop 0
	v_addc_co_u32_e32 v3, vcc, 0, v3, vcc
	global_store_dwordx2 v[2:3], v[0:1], off
	s_addk_i32 s8, 0x1400
	s_cmpk_lt_i32 s8, 0x2000
	s_cbranch_scc1 .LBB0_590
	s_branch .LBB0_591
	v_add_u32_e32 v0, 0x200, v53
	v_ashrrev_i32_e32 v48, 6, v0
	v_ashrrev_i32_e32 v49, 31, v48
	v_lshlrev_b64 v[0:1], 13, v[48:49]
	v_lshl_add_u64 v[50:51], v[44:45], 0, v[0:1]
	v_add_co_u32_e32 v4, vcc, s10, v50
	s_mov_b32 s10, 0x200000
	s_nop 0
	v_addc_co_u32_e32 v5, vcc, 0, v51, vcc
	v_add_co_u32_e32 v8, vcc, s10, v50
	s_mov_b32 s10, 0x300000
	s_nop 0
	v_addc_co_u32_e32 v9, vcc, 0, v51, vcc
	v_add_co_u32_e32 v12, vcc, s10, v50
	s_mov_b32 s10, 0x400000
	s_nop 0
	v_addc_co_u32_e32 v13, vcc, 0, v51, vcc
	v_add_co_u32_e32 v16, vcc, s10, v50
	s_mov_b32 s10, 0x500000
	s_nop 0
	v_addc_co_u32_e32 v17, vcc, 0, v51, vcc
	v_add_co_u32_e32 v20, vcc, s10, v50
	s_mov_b32 s10, 0x600000
	s_nop 0
	v_addc_co_u32_e32 v21, vcc, 0, v51, vcc
	v_add_co_u32_e32 v24, vcc, s10, v50
	global_load_dwordx4 v[0:3], v[50:51], off
	s_nop 0
	v_addc_co_u32_e32 v25, vcc, 0, v51, vcc
	s_mov_b32 s10, 0x700000
	global_load_dwordx4 v[4:7], v[4:5], off
	v_add_co_u32_e32 v28, vcc, s10, v50
	global_load_dwordx4 v[8:11], v[8:9], off
	s_nop 0
	v_addc_co_u32_e32 v29, vcc, 0, v51, vcc
	s_mov_b32 s10, 0x800000
	global_load_dwordx4 v[12:15], v[12:13], off
	v_add_co_u32_e32 v32, vcc, s10, v50
	global_load_dwordx4 v[16:19], v[16:17], off
	s_nop 0
	v_addc_co_u32_e32 v33, vcc, 0, v51, vcc
	s_mov_b32 s10, 0x900000
	global_load_dwordx4 v[20:23], v[20:21], off
	v_add_co_u32_e32 v36, vcc, s10, v50
	global_load_dwordx4 v[24:27], v[24:25], off
	s_nop 0
	v_addc_co_u32_e32 v37, vcc, 0, v51, vcc
	s_mov_b32 s10, 0xa00000
	global_load_dwordx4 v[28:31], v[28:29], off
	v_add_co_u32_e32 v40, vcc, s10, v50
	global_load_dwordx4 v[32:35], v[32:33], off
	s_nop 0
	v_addc_co_u32_e32 v41, vcc, 0, v51, vcc
	s_mov_b32 s10, 0xb00000
	global_load_dwordx4 v[36:39], v[36:37], off
	v_add_co_u32_e32 v50, vcc, s10, v50
	global_load_dwordx4 v[40:43], v[40:41], off
	s_nop 0
	v_addc_co_u32_e32 v51, vcc, 0, v51, vcc
	global_load_dwordx4 v[54:57], v[50:51], off
	s_waitcnt vmcnt(11)
	v_pk_add_f32 v[2:3], v[2:3], 0 op_sel_hi:[1,0]
	v_pk_add_f32 v[0:1], v[0:1], 0 op_sel_hi:[1,0]
	s_waitcnt vmcnt(10)
	v_pk_add_f32 v[2:3], v[2:3], v[6:7]
	v_pk_add_f32 v[0:1], v[0:1], v[4:5]
	s_waitcnt vmcnt(9)
	v_pk_add_f32 v[2:3], v[2:3], v[10:11]
	v_pk_add_f32 v[0:1], v[0:1], v[8:9]
	s_waitcnt vmcnt(8)
	v_pk_add_f32 v[2:3], v[2:3], v[14:15]
	v_pk_add_f32 v[0:1], v[0:1], v[12:13]
	s_waitcnt vmcnt(7)
	v_pk_add_f32 v[2:3], v[2:3], v[18:19]
	v_pk_add_f32 v[0:1], v[0:1], v[16:17]
	s_waitcnt vmcnt(6)
	v_pk_add_f32 v[2:3], v[2:3], v[22:23]
	v_pk_add_f32 v[0:1], v[0:1], v[20:21]
	s_waitcnt vmcnt(5)
	v_pk_add_f32 v[2:3], v[2:3], v[26:27]
	v_pk_add_f32 v[0:1], v[0:1], v[24:25]
	s_waitcnt vmcnt(4)
	v_pk_add_f32 v[2:3], v[2:3], v[30:31]
	v_pk_add_f32 v[0:1], v[0:1], v[28:29]
	s_waitcnt vmcnt(3)
	v_pk_add_f32 v[2:3], v[2:3], v[34:35]
	v_pk_add_f32 v[0:1], v[0:1], v[32:33]
	s_waitcnt vmcnt(2)
	v_pk_add_f32 v[2:3], v[2:3], v[38:39]
	v_pk_add_f32 v[0:1], v[0:1], v[36:37]
	s_waitcnt vmcnt(1)
	v_pk_add_f32 v[2:3], v[2:3], v[42:43]
	v_pk_add_f32 v[0:1], v[0:1], v[40:41]
	s_waitcnt vmcnt(0)
	v_pk_add_f32 v[2:3], v[2:3], v[56:57]
	v_pk_add_f32 v[0:1], v[0:1], v[54:55]
	s_nop 0
	s_nop 1
	v_cvt_pk_bf16_f32 v0, v0, v1
	s_nop 1
	v_cvt_pk_bf16_f32 v1, v2, v3
	v_lshlrev_b64 v[2:3], 12, v[48:49]
	v_lshl_add_u64 v[2:3], v[46:47], 0, v[2:3]
	v_add_co_u32_e32 v2, vcc, 0x2000000, v2
	s_nop 1
	v_addc_co_u32_e32 v3, vcc, 0, v3, vcc
	global_store_dwordx2 v[2:3], v[0:1], off
	s_cbranch_scc0 .LBB0_590

.LBB0_816:
	s_lshl_b64 s[10:11], s[2:3], 20
	s_add_u32 s10, s12, s10
	s_addc_u32 s11, s13, s11
	v_lshl_add_u64 v[64:65], s[10:11], 0, v[140:141]
	v_lshlrev_b64 v[66:67], 2, v[152:153]
	v_lshl_add_u64 v[64:65], v[64:65], 0, v[66:67]
	global_store_dwordx4 v[64:65], v[60:63], off
	global_store_dwordx4 v[64:65], v[56:59], off offset:16
	global_store_dwordx4 v[64:65], v[36:39], off offset:512
	global_store_dwordx4 v[64:65], v[32:35], off offset:528
	s_nop 1
	v_lshl_add_u64 v[32:33], s[10:11], 0, v[142:143]
	v_lshl_add_u64 v[32:33], v[32:33], 0, v[66:67]
	global_store_dwordx4 v[32:33], v[52:55], off
	global_store_dwordx4 v[32:33], v[48:51], off offset:16
	global_store_dwordx4 v[32:33], v[20:23], off offset:512
	global_store_dwordx4 v[32:33], v[16:19], off offset:528
	s_nop 1
	v_lshl_add_u64 v[16:17], s[10:11], 0, v[144:145]
	v_lshl_add_u64 v[16:17], v[16:17], 0, v[66:67]
	global_store_dwordx4 v[16:17], v[44:47], off
	global_store_dwordx4 v[16:17], v[40:43], off offset:16
	global_store_dwordx4 v[16:17], v[12:15], off offset:512
	global_store_dwordx4 v[16:17], v[8:11], off offset:528
	s_nop 1
	v_lshl_add_u64 v[8:9], s[10:11], 0, v[146:147]
	v_lshl_add_u64 v[8:9], v[8:9], 0, v[66:67]
	global_store_dwordx4 v[8:9], v[28:31], off
	global_store_dwordx4 v[8:9], v[24:27], off offset:16
	global_store_dwordx4 v[8:9], v[4:7], off offset:512
	global_store_dwordx4 v[8:9], v[0:3], off offset:528
	s_waitcnt vmcnt(0)
	s_waitcnt vmcnt(0)
	s_barrier
	s_and_saveexec_b64 s[10:11], s[18:19]
	s_cbranch_execz .LBB0_818
	s_lshl_b32 s14, s0, 6
	s_ashr_i32 s15, s14, 31
	s_lshl_b64 s[14:15], s[14:15], 2
	s_add_u32 s14, s36, s14
	s_addc_u32 s15, s37, s15
	buffer_wbl2 sc1
	s_waitcnt vmcnt(0)
	v_mov_b64_e32 v[0:1], s[14:15]
	flat_atomic_add v0, v[0:1], v158 sc0
	s_waitcnt vmcnt(0) lgkmcnt(0)
	ds_write_b32 v137, v0
	v_mov_b64_e32 v[2:3], s[14:15]
.Lsl_spin_out2:
	global_load_dword v4, v[2:3], off sc1
	s_waitcnt vmcnt(0)
	v_cmp_gt_u32_e32 vcc, 8, v4
	s_cbranch_vccz .Lsl_go_out2
	s_sleep 1
	s_branch .Lsl_spin_out2
.Lsl_go_out2:
.LBB0_818:
	s_or_b64 exec, exec, s[10:11]
	s_waitcnt lgkmcnt(0)
	s_barrier
	ds_read_b32 v0, v137
	s_waitcnt lgkmcnt(0)
	v_readfirstlane_b32 s2, v0
	v_mov_b32_e32 v8, v183
	buffer_inv sc1
	s_waitcnt vmcnt(0)
	s_lshl_b32 s0, s0, 2
	v_lshlrev_b32_e32 v0, 2, v8
	v_and_b32_e32 v0, 0xfc, v0
	v_or_b32_e32 v4, s1, v0
	s_ashr_i32 s1, s0, 31
	s_lshl_b64 s[0:1], s[0:1], 2
	v_and_b32_e32 v2, 63, v8
	s_add_u32 s0, s16, s0
	v_ashrrev_i32_e32 v5, 31, v4
	s_addc_u32 s1, s17, s1
	v_lshlrev_b32_e32 v136, 2, v2
	v_cmp_gt_u32_e32 vcc, 4, v2
	s_lshl_b32 s2, s2, 9
	v_cmp_eq_u32_e64 s[10:11], 0, v2
	v_lshl_add_u64 v[0:1], v[4:5], 2, s[12:13]
	v_lshl_add_u64 v[2:3], s[0:1], 0, v[136:137]
	v_lshl_add_u64 v[4:5], v[4:5], 1, s[6:7]
	s_cmpk_lt_i32 s2, 0x2000
	s_cbranch_scc1 .LBB0_821
	s_branch .LBB0_829

.LBB0_823:
	s_or_b64 exec, exec, s[0:1]
	s_addk_i32 s2, 0x1000
	s_cmpk_lt_i32 s2, 0x2000
	s_cbranch_scc1 .LBB0_821
	s_branch .LBB0_829
	v_add_u32_e32 v6, 0x200, v9
	v_ashrrev_i32_e32 v16, 6, v6
	s_waitcnt lgkmcnt(0)
	v_ashrrev_i32_e32 v17, 31, v16
	v_add_u32_e32 v6, 0x2000, v16
	v_lshlrev_b64 v[16:17], 13, v[16:17]
	v_lshl_add_u64 v[44:45], v[0:1], 0, v[16:17]
	v_add_co_u32_e64 v20, s[0:1], s63, v44
	v_ashrrev_i32_e32 v7, 31, v6
	s_nop 0
	v_addc_co_u32_e64 v21, s[0:1], 0, v45, s[0:1]
	v_add_co_u32_e64 v24, s[0:1], s64, v44
	v_lshlrev_b64 v[18:19], 12, v[6:7]
	s_nop 0
	v_addc_co_u32_e64 v25, s[0:1], 0, v45, s[0:1]
	v_add_co_u32_e64 v28, s[0:1], s65, v44
	v_lshl_add_u64 v[48:49], v[4:5], 0, v[18:19]
	s_nop 0
	v_addc_co_u32_e64 v29, s[0:1], 0, v45, s[0:1]
	v_add_co_u32_e64 v32, s[0:1], s66, v44
	global_load_dwordx2 v[50:51], v[48:49], off
	global_load_dwordx4 v[16:19], v[44:45], off
	v_addc_co_u32_e64 v33, s[0:1], 0, v45, s[0:1]
	v_add_co_u32_e64 v36, s[0:1], s67, v44
	global_load_dwordx4 v[20:23], v[20:21], off
	s_nop 0
	global_load_dwordx4 v[24:27], v[24:25], off
	v_addc_co_u32_e64 v37, s[0:1], 0, v45, s[0:1]
	v_add_co_u32_e64 v40, s[0:1], s74, v44
	global_load_dwordx4 v[28:31], v[28:29], off
	s_nop 0
	global_load_dwordx4 v[32:35], v[32:33], off
	v_addc_co_u32_e64 v41, s[0:1], 0, v45, s[0:1]
	v_add_co_u32_e64 v44, s[0:1], s75, v44
	global_load_dwordx4 v[36:39], v[36:37], off
	s_nop 0
	global_load_dwordx4 v[40:43], v[40:41], off
	v_addc_co_u32_e64 v45, s[0:1], 0, v45, s[0:1]
	global_load_dwordx4 v[44:47], v[44:45], off
	s_waitcnt vmcnt(0)
	v_lshlrev_b32_e32 v52, 16, v50
	v_and_b32_e32 v53, 0xffff0000, v50
	v_lshlrev_b32_e32 v50, 16, v51
	v_and_b32_e32 v51, 0xffff0000, v51
	v_pk_add_f32 v[18:19], v[18:19], v[50:51]
	v_pk_add_f32 v[16:17], v[16:17], v[52:53]
	v_pk_add_f32 v[18:19], v[22:23], v[18:19]
	v_pk_add_f32 v[16:17], v[20:21], v[16:17]
	v_pk_add_f32 v[18:19], v[26:27], v[18:19]
	v_pk_add_f32 v[16:17], v[24:25], v[16:17]
	v_pk_add_f32 v[18:19], v[30:31], v[18:19]
	v_pk_add_f32 v[16:17], v[28:29], v[16:17]
	v_pk_add_f32 v[18:19], v[34:35], v[18:19]
	v_pk_add_f32 v[16:17], v[32:33], v[16:17]
	v_pk_add_f32 v[18:19], v[38:39], v[18:19]
	v_pk_add_f32 v[16:17], v[36:37], v[16:17]
	v_pk_add_f32 v[18:19], v[42:43], v[18:19]
	v_pk_add_f32 v[16:17], v[40:41], v[16:17]
	v_pk_add_f32 v[18:19], v[46:47], v[18:19]
	v_pk_add_f32 v[20:21], v[44:45], v[16:17]
	v_mul_f32_e32 v17, v19, v19
	v_mul_f32_e32 v16, v21, v21
	v_fmac_f32_e32 v16, v20, v20
	v_fmac_f32_e32 v17, v18, v18
	v_add_f32_e32 v16, v16, v17
	ds_bpermute_b32 v17, v10, v16
	s_nop 1
	v_cvt_pk_bf16_f32 v20, v20, v21
	s_nop 1
	v_cvt_pk_bf16_f32 v21, v18, v19
	global_store_dwordx2 v[48:49], v[20:21], off
	s_waitcnt lgkmcnt(0)
	v_add_f32_e32 v16, v16, v17
	ds_bpermute_b32 v17, v11, v16
	s_waitcnt lgkmcnt(0)
	v_add_f32_e32 v16, v16, v17
	ds_bpermute_b32 v17, v12, v16
	s_waitcnt lgkmcnt(0)
	v_add_f32_e32 v16, v16, v17
	ds_bpermute_b32 v17, v13, v16
	s_waitcnt lgkmcnt(0)
	v_add_f32_e32 v16, v16, v17
	ds_bpermute_b32 v17, v14, v16
	s_waitcnt lgkmcnt(0)
	v_add_f32_e32 v16, v16, v17
	ds_bpermute_b32 v17, v15, v16
	s_and_saveexec_b64 s[0:1], vcc
	s_cbranch_execz .LBB0_825
	s_waitcnt lgkmcnt(0)
	v_add_f32_e32 v16, v16, v17
	v_lshlrev_b64 v[6:7], 7, v[6:7]
	v_cndmask_b32_e64 v16, 0, v16, s[10:11]
	v_lshl_add_u64 v[6:7], v[2:3], 0, v[6:7]
	flat_store_dword v[6:7], v16 sc1

.LBB0_829:
	s_waitcnt vmcnt(0)
	s_waitcnt lgkmcnt(0)
	s_barrier
	s_and_saveexec_b64 s[0:1], s[18:19]
	s_cbranch_execz .LBB0_831
	v_mov_b64_e32 v[0:1], s[40:41]
	flat_atomic_add v0, v[0:1], v158 sc0
	s_waitcnt vmcnt(0) lgkmcnt(0)
	v_cmp_eq_u32_e32 vcc, 63, v0
	s_nop 1
	v_cndmask_b32_e64 v0, 0, 1, vcc
	ds_write_b32 v137, v0

.LBB0_1080:
	s_lshl_b64 s[0:1], s[2:3], 20
	s_add_u32 s0, s16, s0
	s_addc_u32 s1, s17, s1
	v_lshl_add_u64 v[64:65], s[0:1], 0, v[140:141]
	v_lshlrev_b64 v[66:67], 2, v[152:153]
	v_lshl_add_u64 v[64:65], v[64:65], 0, v[66:67]
	global_store_dwordx4 v[64:65], v[60:63], off
	global_store_dwordx4 v[64:65], v[56:59], off offset:16
	global_store_dwordx4 v[64:65], v[36:39], off offset:512
	global_store_dwordx4 v[64:65], v[32:35], off offset:528
	s_nop 1
	v_lshl_add_u64 v[32:33], s[0:1], 0, v[142:143]
	v_lshl_add_u64 v[32:33], v[32:33], 0, v[66:67]
	global_store_dwordx4 v[32:33], v[52:55], off
	global_store_dwordx4 v[32:33], v[48:51], off offset:16
	global_store_dwordx4 v[32:33], v[20:23], off offset:512
	global_store_dwordx4 v[32:33], v[16:19], off offset:528
	s_nop 1
	v_lshl_add_u64 v[16:17], s[0:1], 0, v[144:145]
	v_lshl_add_u64 v[16:17], v[16:17], 0, v[66:67]
	global_store_dwordx4 v[16:17], v[44:47], off
	global_store_dwordx4 v[16:17], v[40:43], off offset:16
	global_store_dwordx4 v[16:17], v[12:15], off offset:512
	global_store_dwordx4 v[16:17], v[8:11], off offset:528
	s_nop 1
	v_lshl_add_u64 v[8:9], s[0:1], 0, v[146:147]
	v_lshl_add_u64 v[8:9], v[8:9], 0, v[66:67]
	global_store_dwordx4 v[8:9], v[28:31], off
	global_store_dwordx4 v[8:9], v[24:27], off offset:16
	global_store_dwordx4 v[8:9], v[4:7], off offset:512
	global_store_dwordx4 v[8:9], v[0:3], off offset:528
	s_waitcnt vmcnt(0)
	s_waitcnt vmcnt(0)
	s_barrier
	s_and_saveexec_b64 s[0:1], s[18:19]
	s_cbranch_execz .LBB0_1082
	s_lshl_b32 s8, s57, 6
	s_ashr_i32 s9, s8, 31
	s_lshl_b64 s[8:9], s[8:9], 2
	s_add_u32 s8, s42, s8
	s_addc_u32 s9, s43, s9
	buffer_wbl2 sc1
	s_waitcnt vmcnt(0)
	v_mov_b64_e32 v[0:1], s[8:9]
	flat_atomic_add v0, v[0:1], v158 sc0
	s_waitcnt vmcnt(0) lgkmcnt(0)
	ds_write_b32 v137, v0
	v_mov_b64_e32 v[2:3], s[8:9]
.Lsl_spin_dn3:
	global_load_dword v4, v[2:3], off sc1
	s_waitcnt vmcnt(0)
	v_cmp_gt_u32_e32 vcc, 22, v4
	s_cbranch_vccz .Lsl_go_dn3
	s_sleep 1
	s_branch .Lsl_spin_dn3
.Lsl_go_dn3:
.LBB0_1082:
	s_or_b64 exec, exec, s[0:1]
	s_waitcnt lgkmcnt(0)
	s_barrier
	ds_read_b32 v0, v137
	s_waitcnt lgkmcnt(0)
	v_readfirstlane_b32 s2, v0
	v_mov_b32_e32 v16, v183
	s_lshl_b32 s0, s57, 2
	buffer_inv sc1
	s_waitcnt vmcnt(0)
	s_ashr_i32 s1, s0, 31
	v_lshlrev_b32_e32 v0, 2, v16
	v_and_b32_e32 v0, 0xfc, v0
	s_lshl_b64 s[0:1], s[0:1], 2
	v_and_b32_e32 v2, 63, v16
	v_or_b32_e32 v4, s59, v0
	s_add_u32 s0, s26, s0
	v_ashrrev_i32_e32 v5, 31, v4
	s_addc_u32 s1, s27, s1
	v_lshlrev_b32_e32 v136, 2, v2
	v_cmp_gt_u32_e32 vcc, 4, v2
	s_lshl_b32 s2, s2, 9
	v_cmp_eq_u32_e64 s[14:15], 0, v2
	v_lshl_add_u64 v[0:1], v[4:5], 2, s[16:17]
	v_lshl_add_u64 v[2:3], s[0:1], 0, v[136:137]
	v_lshl_add_u64 v[4:5], v[4:5], 1, s[6:7]
	s_cmpk_lt_i32 s2, 0x2000
	s_cbranch_scc1 .LBB0_1085
	s_branch .LBB0_1093

.LBB0_1087:
	s_or_b64 exec, exec, s[0:1]
	s_addk_i32 s2, 0x2c00
	s_cmpk_lt_i32 s2, 0x2000
	s_cbranch_scc1 .LBB0_1085
	s_branch .LBB0_1093
	v_add_u32_e32 v6, 0x200, v17
	v_ashrrev_i32_e32 v10, 6, v6
	v_add_u32_e32 v6, 0x2000, v10
	v_ashrrev_i32_e32 v7, 31, v6
	s_waitcnt lgkmcnt(0)
	v_lshlrev_b64 v[8:9], 12, v[6:7]
	v_lshl_add_u64 v[8:9], v[4:5], 0, v[8:9]
	global_load_dwordx2 v[12:13], v[8:9], off
	v_ashrrev_i32_e32 v11, 31, v10
	v_lshlrev_b64 v[10:11], 13, v[10:11]
	v_lshl_add_u64 v[14:15], v[0:1], 0, v[10:11]
	v_add_co_u32_e64 v24, s[0:1], s88, v14
	s_nop 1
	v_addc_co_u32_e64 v25, s[0:1], 0, v15, s[0:1]
	v_add_co_u32_e64 v28, s[0:1], s89, v14
	global_load_dwordx4 v[24:27], v[24:25], off
	s_nop 0
	v_addc_co_u32_e64 v29, s[0:1], 0, v15, s[0:1]
	v_add_co_u32_e64 v32, s[0:1], s90, v14
	global_load_dwordx4 v[28:31], v[28:29], off
	s_nop 0
	v_addc_co_u32_e64 v33, s[0:1], 0, v15, s[0:1]
	v_add_co_u32_e64 v36, s[0:1], s91, v14
	global_load_dwordx4 v[32:35], v[32:33], off
	s_nop 0
	v_addc_co_u32_e64 v37, s[0:1], 0, v15, s[0:1]
	v_add_co_u32_e64 v40, s[0:1], s92, v14
	global_load_dwordx4 v[36:39], v[36:37], off
	s_nop 0
	v_addc_co_u32_e64 v41, s[0:1], 0, v15, s[0:1]
	v_add_co_u32_e64 v44, s[0:1], s93, v14
	global_load_dwordx4 v[40:43], v[40:41], off
	s_nop 0
	v_addc_co_u32_e64 v45, s[0:1], 0, v15, s[0:1]
	v_add_co_u32_e64 v48, s[0:1], s94, v14
	global_load_dwordx4 v[44:47], v[44:45], off
	s_nop 0
	v_addc_co_u32_e64 v49, s[0:1], 0, v15, s[0:1]
	v_add_co_u32_e64 v52, s[0:1], s95, v14
	global_load_dwordx4 v[48:51], v[48:49], off
	s_nop 0
	v_addc_co_u32_e64 v53, s[0:1], 0, v15, s[0:1]
	v_add_co_u32_e64 v56, s[0:1], s96, v14
	global_load_dwordx4 v[52:55], v[52:53], off
	s_nop 0
	v_addc_co_u32_e64 v57, s[0:1], 0, v15, s[0:1]
	v_add_co_u32_e64 v60, s[0:1], s97, v14
	global_load_dwordx4 v[56:59], v[56:57], off
	s_nop 0
	v_addc_co_u32_e64 v61, s[0:1], 0, v15, s[0:1]
	v_add_co_u32_e64 v64, s[0:1], s50, v14
	global_load_dwordx4 v[60:63], v[60:61], off
	s_nop 0
	v_addc_co_u32_e64 v65, s[0:1], 0, v15, s[0:1]
	global_load_dwordx4 v[64:67], v[64:65], off
	s_waitcnt vmcnt(0)
	v_lshlrev_b32_e32 v68, 16, v12
	v_and_b32_e32 v69, 0xffff0000, v12
	v_lshlrev_b32_e32 v70, 16, v13
	v_and_b32_e32 v71, 0xffff0000, v13
	global_load_dwordx4 v[10:13], v[14:15], off
	s_waitcnt vmcnt(0)
	v_pk_add_f32 v[12:13], v[12:13], v[70:71]
	v_pk_add_f32 v[10:11], v[10:11], v[68:69]
	v_pk_add_f32 v[12:13], v[26:27], v[12:13]
	v_pk_add_f32 v[10:11], v[24:25], v[10:11]
	v_pk_add_f32 v[12:13], v[30:31], v[12:13]
	v_pk_add_f32 v[10:11], v[28:29], v[10:11]
	v_pk_add_f32 v[12:13], v[34:35], v[12:13]
	v_pk_add_f32 v[10:11], v[32:33], v[10:11]
	v_pk_add_f32 v[12:13], v[38:39], v[12:13]
	v_pk_add_f32 v[10:11], v[36:37], v[10:11]
	v_pk_add_f32 v[12:13], v[42:43], v[12:13]
	v_pk_add_f32 v[10:11], v[40:41], v[10:11]
	v_pk_add_f32 v[12:13], v[46:47], v[12:13]
	v_pk_add_f32 v[10:11], v[44:45], v[10:11]
	v_pk_add_f32 v[12:13], v[50:51], v[12:13]
	v_pk_add_f32 v[10:11], v[48:49], v[10:11]
	v_pk_add_f32 v[12:13], v[54:55], v[12:13]
	v_pk_add_f32 v[10:11], v[52:53], v[10:11]
	v_pk_add_f32 v[12:13], v[58:59], v[12:13]
	v_pk_add_f32 v[10:11], v[56:57], v[10:11]
	v_pk_add_f32 v[12:13], v[62:63], v[12:13]
	v_pk_add_f32 v[24:25], v[60:61], v[10:11]
	v_pk_add_f32 v[10:11], v[66:67], v[12:13]
	v_pk_add_f32 v[12:13], v[64:65], v[24:25]
	v_add_co_u32_e64 v24, s[0:1], s51, v14
	s_nop 1
	v_addc_co_u32_e64 v25, s[0:1], 0, v15, s[0:1]
	v_add_co_u32_e64 v28, s[0:1], s78, v14
	global_load_dwordx4 v[24:27], v[24:25], off
	s_nop 0
	v_addc_co_u32_e64 v29, s[0:1], 0, v15, s[0:1]
	v_add_co_u32_e64 v32, s[0:1], s79, v14
	global_load_dwordx4 v[28:31], v[28:29], off
	s_nop 0
	v_addc_co_u32_e64 v33, s[0:1], 0, v15, s[0:1]
	v_add_co_u32_e64 v36, s[0:1], s80, v14
	global_load_dwordx4 v[32:35], v[32:33], off
	s_nop 0
	v_addc_co_u32_e64 v37, s[0:1], 0, v15, s[0:1]
	v_add_co_u32_e64 v40, s[0:1], s81, v14
	global_load_dwordx4 v[36:39], v[36:37], off
	s_nop 0
	v_addc_co_u32_e64 v41, s[0:1], 0, v15, s[0:1]
	v_add_co_u32_e64 v44, s[0:1], s52, v14
	global_load_dwordx4 v[40:43], v[40:41], off
	s_nop 0
	v_addc_co_u32_e64 v45, s[0:1], 0, v15, s[0:1]
	v_add_co_u32_e64 v48, s[0:1], s4, v14
	global_load_dwordx4 v[44:47], v[44:45], off
	s_nop 0
	v_addc_co_u32_e64 v49, s[0:1], 0, v15, s[0:1]
	v_add_co_u32_e64 v52, s[0:1], s5, v14
	global_load_dwordx4 v[48:51], v[48:49], off
	s_nop 0
	v_addc_co_u32_e64 v53, s[0:1], 0, v15, s[0:1]
	v_add_co_u32_e64 v56, s[0:1], s21, v14
	global_load_dwordx4 v[52:55], v[52:53], off
	s_nop 0
	v_addc_co_u32_e64 v57, s[0:1], 0, v15, s[0:1]
	v_add_co_u32_e64 v14, s[0:1], s24, v14
	global_load_dwordx4 v[56:59], v[56:57], off
	s_nop 0
	v_addc_co_u32_e64 v15, s[0:1], 0, v15, s[0:1]
	global_load_dwordx4 v[60:63], v[14:15], off
	s_waitcnt vmcnt(9)
	v_pk_add_f32 v[10:11], v[26:27], v[10:11]
	v_pk_add_f32 v[12:13], v[24:25], v[12:13]
	s_waitcnt vmcnt(8)
	v_pk_add_f32 v[10:11], v[30:31], v[10:11]
	v_pk_add_f32 v[12:13], v[28:29], v[12:13]
	s_waitcnt vmcnt(7)
	v_pk_add_f32 v[10:11], v[34:35], v[10:11]
	v_pk_add_f32 v[12:13], v[32:33], v[12:13]
	s_waitcnt vmcnt(6)
	v_pk_add_f32 v[10:11], v[38:39], v[10:11]
	v_pk_add_f32 v[12:13], v[36:37], v[12:13]
	s_waitcnt vmcnt(5)
	v_pk_add_f32 v[10:11], v[42:43], v[10:11]
	v_pk_add_f32 v[12:13], v[40:41], v[12:13]
	s_waitcnt vmcnt(4)
	v_pk_add_f32 v[10:11], v[46:47], v[10:11]
	v_pk_add_f32 v[12:13], v[44:45], v[12:13]
	s_waitcnt vmcnt(3)
	v_pk_add_f32 v[10:11], v[50:51], v[10:11]
	v_pk_add_f32 v[12:13], v[48:49], v[12:13]
	s_waitcnt vmcnt(2)
	v_pk_add_f32 v[10:11], v[54:55], v[10:11]
	v_pk_add_f32 v[12:13], v[52:53], v[12:13]
	s_waitcnt vmcnt(1)
	v_pk_add_f32 v[10:11], v[58:59], v[10:11]
	v_pk_add_f32 v[12:13], v[56:57], v[12:13]
	s_waitcnt vmcnt(0)
	v_pk_add_f32 v[10:11], v[62:63], v[10:11]
	v_pk_add_f32 v[12:13], v[60:61], v[12:13]
	s_nop 0
	s_nop 1
	v_cvt_pk_bf16_f32 v14, v12, v13
	s_nop 1
	v_cvt_pk_bf16_f32 v15, v10, v11
	global_store_dwordx2 v[8:9], v[14:15], off
	v_mul_f32_e32 v8, v13, v13
	v_mul_f32_e32 v9, v11, v11
	v_fmac_f32_e32 v8, v12, v12
	v_fmac_f32_e32 v9, v10, v10
	v_add_f32_e32 v8, v8, v9
	ds_bpermute_b32 v9, v18, v8
	s_waitcnt lgkmcnt(0)
	v_add_f32_e32 v8, v8, v9
	ds_bpermute_b32 v9, v19, v8
	s_waitcnt lgkmcnt(0)
	v_add_f32_e32 v8, v8, v9
	ds_bpermute_b32 v9, v20, v8
	s_waitcnt lgkmcnt(0)
	v_add_f32_e32 v8, v8, v9
	ds_bpermute_b32 v9, v21, v8
	s_waitcnt lgkmcnt(0)
	v_add_f32_e32 v8, v8, v9
	ds_bpermute_b32 v9, v22, v8
	s_waitcnt lgkmcnt(0)
	v_add_f32_e32 v8, v8, v9
	ds_bpermute_b32 v9, v23, v8
	s_and_saveexec_b64 s[0:1], vcc
	s_cbranch_execz .LBB0_1089
	s_waitcnt lgkmcnt(0)
	v_add_f32_e32 v8, v8, v9
	v_lshlrev_b64 v[6:7], 7, v[6:7]
	v_cndmask_b32_e64 v8, 0, v8, s[14:15]
	v_lshl_add_u64 v[6:7], v[2:3], 0, v[6:7]
	flat_store_dword v[6:7], v8 sc1

.LBB0_1093:
	s_waitcnt vmcnt(0)
	s_waitcnt lgkmcnt(0)
	s_barrier
	s_and_saveexec_b64 s[0:1], s[18:19]
	s_cbranch_execz .LBB0_1095
	v_mov_b64_e32 v[0:1], s[48:49]
	flat_atomic_add v0, v[0:1], v158 sc0
	s_waitcnt vmcnt(0) lgkmcnt(0)
	v_cmp_eq_u32_e32 vcc, 175, v0
	s_nop 1
	v_cndmask_b32_e64 v0, 0, 1, vcc
	ds_write_b32 v137, v0

.LBB0_1520:
	s_and_b64 vcc, exec, s[8:9]
	s_cbranch_vccz .LBB0_1526
	v_lshl_add_u64 v[66:67], v[162:163], 0, v[174:175]
	global_load_dwordx2 v[68:69], v[66:67], off
	s_add_i32 s4, s4, s81
	s_lshl_b64 s[8:9], s[4:5], 20
	s_add_u32 s64, s10, s8
	s_addc_u32 s65, s11, s9
	v_lshl_add_u64 v[70:71], s[64:65], 0, v[154:155]
	v_lshlrev_b64 v[64:65], 2, v[174:175]
	v_lshl_add_u64 v[70:71], v[70:71], 0, v[64:65]
	s_waitcnt vmcnt(0)
	v_cvt_f32_ubyte3_e32 v73, v68
	v_cvt_f32_ubyte2_e32 v72, v68
	v_cvt_f32_ubyte1_e32 v75, v68
	v_cvt_f32_ubyte0_e32 v74, v68
	v_pk_mul_f32 v[74:75], v[74:75], s[36:37] op_sel_hi:[1,0]
	v_pk_mul_f32 v[72:73], v[72:73], s[36:37] op_sel_hi:[1,0]
	v_pk_mul_f32 v[60:61], v[60:61], v[74:75]
	v_pk_mul_f32 v[62:63], v[62:63], v[72:73]
	global_store_dwordx4 v[70:71], v[60:63], off
	s_nop 1
	v_cvt_f32_ubyte3_e32 v61, v69
	v_cvt_f32_ubyte2_e32 v60, v69
	v_cvt_f32_ubyte1_e32 v63, v69
	v_cvt_f32_ubyte0_e32 v62, v69
	v_pk_mul_f32 v[62:63], v[62:63], s[36:37] op_sel_hi:[1,0]
	v_pk_mul_f32 v[60:61], v[60:61], s[36:37] op_sel_hi:[1,0]
	v_pk_mul_f32 v[56:57], v[56:57], v[62:63]
	v_pk_mul_f32 v[58:59], v[58:59], v[60:61]
	global_store_dwordx4 v[70:71], v[56:59], off offset:16
	global_load_dwordx2 v[56:57], v[66:67], off offset:128
	s_waitcnt vmcnt(0)
	v_cvt_f32_ubyte1_e32 v61, v56
	v_cvt_f32_ubyte3_e32 v59, v56
	v_cvt_f32_ubyte2_e32 v58, v56
	v_cvt_f32_ubyte0_e32 v60, v56
	v_pk_mul_f32 v[60:61], v[60:61], s[36:37] op_sel_hi:[1,0]
	v_pk_mul_f32 v[58:59], v[58:59], s[36:37] op_sel_hi:[1,0]
	v_pk_mul_f32 v[52:53], v[52:53], v[60:61]
	v_pk_mul_f32 v[54:55], v[54:55], v[58:59]
	global_store_dwordx4 v[70:71], v[52:55], off offset:512
	s_nop 1
	v_cvt_f32_ubyte3_e32 v53, v57
	v_cvt_f32_ubyte2_e32 v52, v57
	v_cvt_f32_ubyte1_e32 v55, v57
	v_cvt_f32_ubyte0_e32 v54, v57
	v_pk_mul_f32 v[54:55], v[54:55], s[36:37] op_sel_hi:[1,0]
	v_pk_mul_f32 v[52:53], v[52:53], s[36:37] op_sel_hi:[1,0]
	v_pk_mul_f32 v[48:49], v[48:49], v[54:55]
	v_pk_mul_f32 v[50:51], v[50:51], v[52:53]
	global_store_dwordx4 v[70:71], v[48:51], off offset:528
	v_lshl_add_u64 v[52:53], s[64:65], 0, v[156:157]
	v_lshl_add_u64 v[52:53], v[52:53], 0, v[64:65]
	v_lshl_add_u64 v[48:49], v[164:165], 0, v[174:175]
	global_load_dwordx2 v[50:51], v[48:49], off
	s_waitcnt vmcnt(0)
	v_cvt_f32_ubyte3_e32 v55, v50
	v_cvt_f32_ubyte2_e32 v54, v50
	v_cvt_f32_ubyte1_e32 v57, v50
	v_cvt_f32_ubyte0_e32 v56, v50
	v_pk_mul_f32 v[56:57], v[56:57], s[36:37] op_sel_hi:[1,0]
	v_pk_mul_f32 v[54:55], v[54:55], s[36:37] op_sel_hi:[1,0]
	v_pk_mul_f32 v[44:45], v[44:45], v[56:57]
	v_pk_mul_f32 v[46:47], v[46:47], v[54:55]
	global_store_dwordx4 v[52:53], v[44:47], off
	s_nop 1
	v_cvt_f32_ubyte3_e32 v45, v51
	v_cvt_f32_ubyte2_e32 v44, v51
	v_cvt_f32_ubyte1_e32 v47, v51
	v_cvt_f32_ubyte0_e32 v46, v51
	v_pk_mul_f32 v[46:47], v[46:47], s[36:37] op_sel_hi:[1,0]
	v_pk_mul_f32 v[44:45], v[44:45], s[36:37] op_sel_hi:[1,0]
	v_pk_mul_f32 v[40:41], v[40:41], v[46:47]
	v_pk_mul_f32 v[42:43], v[42:43], v[44:45]
	global_store_dwordx4 v[52:53], v[40:43], off offset:16
	global_load_dwordx2 v[40:41], v[48:49], off offset:128
	s_waitcnt vmcnt(0)
	v_cvt_f32_ubyte1_e32 v45, v40
	v_cvt_f32_ubyte3_e32 v43, v40
	v_cvt_f32_ubyte2_e32 v42, v40
	v_cvt_f32_ubyte0_e32 v44, v40
	v_pk_mul_f32 v[44:45], v[44:45], s[36:37] op_sel_hi:[1,0]
	v_pk_mul_f32 v[42:43], v[42:43], s[36:37] op_sel_hi:[1,0]
	v_pk_mul_f32 v[36:37], v[36:37], v[44:45]
	v_pk_mul_f32 v[38:39], v[38:39], v[42:43]
	global_store_dwordx4 v[52:53], v[36:39], off offset:512
	s_nop 1
	v_cvt_f32_ubyte3_e32 v37, v41
	v_cvt_f32_ubyte2_e32 v36, v41
	v_cvt_f32_ubyte1_e32 v39, v41
	v_cvt_f32_ubyte0_e32 v38, v41
	v_pk_mul_f32 v[38:39], v[38:39], s[36:37] op_sel_hi:[1,0]
	v_pk_mul_f32 v[36:37], v[36:37], s[36:37] op_sel_hi:[1,0]
	v_pk_mul_f32 v[32:33], v[32:33], v[38:39]
	v_pk_mul_f32 v[34:35], v[34:35], v[36:37]
	global_store_dwordx4 v[52:53], v[32:35], off offset:528
	v_lshl_add_u64 v[36:37], s[64:65], 0, v[158:159]
	v_lshl_add_u64 v[36:37], v[36:37], 0, v[64:65]
	v_lshl_add_u64 v[32:33], v[166:167], 0, v[174:175]
	global_load_dwordx2 v[34:35], v[32:33], off
	s_waitcnt vmcnt(0)
	v_cvt_f32_ubyte3_e32 v39, v34
	v_cvt_f32_ubyte2_e32 v38, v34
	v_cvt_f32_ubyte1_e32 v41, v34
	v_cvt_f32_ubyte0_e32 v40, v34
	v_pk_mul_f32 v[40:41], v[40:41], s[36:37] op_sel_hi:[1,0]
	v_pk_mul_f32 v[38:39], v[38:39], s[36:37] op_sel_hi:[1,0]
	v_pk_mul_f32 v[28:29], v[28:29], v[40:41]
	v_pk_mul_f32 v[30:31], v[30:31], v[38:39]
	global_store_dwordx4 v[36:37], v[28:31], off
	s_nop 1
	v_cvt_f32_ubyte3_e32 v29, v35
	v_cvt_f32_ubyte2_e32 v28, v35
	v_cvt_f32_ubyte1_e32 v31, v35
	v_cvt_f32_ubyte0_e32 v30, v35
	v_pk_mul_f32 v[30:31], v[30:31], s[36:37] op_sel_hi:[1,0]
	v_pk_mul_f32 v[28:29], v[28:29], s[36:37] op_sel_hi:[1,0]
	v_pk_mul_f32 v[24:25], v[24:25], v[30:31]
	v_pk_mul_f32 v[26:27], v[26:27], v[28:29]
	global_store_dwordx4 v[36:37], v[24:27], off offset:16
	global_load_dwordx2 v[24:25], v[32:33], off offset:128
	s_waitcnt vmcnt(0)
	v_cvt_f32_ubyte1_e32 v29, v24
	v_cvt_f32_ubyte3_e32 v27, v24
	v_cvt_f32_ubyte2_e32 v26, v24
	v_cvt_f32_ubyte0_e32 v28, v24
	v_pk_mul_f32 v[28:29], v[28:29], s[36:37] op_sel_hi:[1,0]
	v_pk_mul_f32 v[26:27], v[26:27], s[36:37] op_sel_hi:[1,0]
	v_pk_mul_f32 v[20:21], v[20:21], v[28:29]
	v_pk_mul_f32 v[22:23], v[22:23], v[26:27]
	global_store_dwordx4 v[36:37], v[20:23], off offset:512
	s_nop 1
	v_cvt_f32_ubyte3_e32 v21, v25
	v_cvt_f32_ubyte2_e32 v20, v25
	v_cvt_f32_ubyte1_e32 v23, v25
	v_cvt_f32_ubyte0_e32 v22, v25
	v_pk_mul_f32 v[22:23], v[22:23], s[36:37] op_sel_hi:[1,0]
	v_pk_mul_f32 v[20:21], v[20:21], s[36:37] op_sel_hi:[1,0]
	v_pk_mul_f32 v[16:17], v[16:17], v[22:23]
	v_pk_mul_f32 v[18:19], v[18:19], v[20:21]
	global_store_dwordx4 v[36:37], v[16:19], off offset:528
	v_lshl_add_u64 v[20:21], s[64:65], 0, v[160:161]
	v_lshl_add_u64 v[20:21], v[20:21], 0, v[64:65]
	v_lshl_add_u64 v[16:17], v[168:169], 0, v[174:175]
	global_load_dwordx2 v[18:19], v[16:17], off
	s_waitcnt vmcnt(0)
	v_cvt_f32_ubyte3_e32 v23, v18
	v_cvt_f32_ubyte2_e32 v22, v18
	v_cvt_f32_ubyte1_e32 v25, v18
	v_cvt_f32_ubyte0_e32 v24, v18
	v_pk_mul_f32 v[24:25], v[24:25], s[36:37] op_sel_hi:[1,0]
	v_pk_mul_f32 v[22:23], v[22:23], s[36:37] op_sel_hi:[1,0]
	v_pk_mul_f32 v[12:13], v[12:13], v[24:25]
	v_pk_mul_f32 v[14:15], v[14:15], v[22:23]
	global_store_dwordx4 v[20:21], v[12:15], off
	s_nop 1
	v_cvt_f32_ubyte3_e32 v13, v19
	v_cvt_f32_ubyte2_e32 v12, v19
	v_cvt_f32_ubyte1_e32 v15, v19
	v_cvt_f32_ubyte0_e32 v14, v19
	v_pk_mul_f32 v[14:15], v[14:15], s[36:37] op_sel_hi:[1,0]
	v_pk_mul_f32 v[12:13], v[12:13], s[36:37] op_sel_hi:[1,0]
	v_pk_mul_f32 v[8:9], v[8:9], v[14:15]
	v_pk_mul_f32 v[10:11], v[10:11], v[12:13]
	global_store_dwordx4 v[20:21], v[8:11], off offset:16
	global_load_dwordx2 v[8:9], v[16:17], off offset:128
	s_waitcnt vmcnt(0)
	v_cvt_f32_ubyte1_e32 v13, v8
	v_cvt_f32_ubyte3_e32 v11, v8
	v_cvt_f32_ubyte2_e32 v10, v8
	v_cvt_f32_ubyte0_e32 v12, v8
	v_pk_mul_f32 v[12:13], v[12:13], s[36:37] op_sel_hi:[1,0]
	v_pk_mul_f32 v[10:11], v[10:11], s[36:37] op_sel_hi:[1,0]
	v_pk_mul_f32 v[4:5], v[4:5], v[12:13]
	v_pk_mul_f32 v[6:7], v[6:7], v[10:11]
	global_store_dwordx4 v[20:21], v[4:7], off offset:512
	s_nop 1
	v_cvt_f32_ubyte3_e32 v5, v9
	v_cvt_f32_ubyte2_e32 v4, v9
	v_cvt_f32_ubyte1_e32 v7, v9
	v_cvt_f32_ubyte0_e32 v6, v9
	v_pk_mul_f32 v[6:7], v[6:7], s[36:37] op_sel_hi:[1,0]
	v_pk_mul_f32 v[4:5], v[4:5], s[36:37] op_sel_hi:[1,0]
	v_pk_mul_f32 v[0:1], v[0:1], v[6:7]
	v_pk_mul_f32 v[2:3], v[2:3], v[4:5]
	global_store_dwordx4 v[20:21], v[0:3], off offset:528
	s_waitcnt vmcnt(0)
	s_barrier
	s_and_saveexec_b64 s[8:9], s[18:19]
	s_cbranch_execz .LBB0_1523
	s_lshl_b32 s64, s84, 6
	s_ashr_i32 s65, s64, 31
	s_lshl_b64 s[64:65], s[64:65], 2
	s_add_u32 s64, s37, s64
	s_addc_u32 s65, s53, s65
	buffer_wbl2 sc1
	s_waitcnt vmcnt(0)
	s_waitcnt vmcnt(0)
	v_mov_b64_e32 v[0:1], s[64:65]
	flat_atomic_add v0, v[0:1], v182 sc0
	s_waitcnt vmcnt(0) lgkmcnt(0)
	ds_write_b32 v145, v0
	v_mov_b64_e32 v[2:3], s[64:65]

.Lsl_go_br4:
.LBB0_1523:
	s_or_b64 exec, exec, s[8:9]
	s_waitcnt lgkmcnt(0)
	s_barrier
	ds_read_b32 v0, v145
	s_waitcnt lgkmcnt(0)
	v_readfirstlane_b32 s4, v0
	v_mov_b32_e32 v52, v183
	s_waitcnt vmcnt(0)
	buffer_inv sc1
	s_waitcnt vmcnt(0)
	s_lshl_b32 s4, s4, 9
	v_lshlrev_b32_e32 v0, 2, v52
	v_and_b32_e32 v0, 0xfc, v0
	v_or_b32_e32 v0, s51, v0
	v_ashrrev_i32_e32 v1, 31, v0
	v_lshl_add_u64 v[44:45], v[0:1], 2, s[10:11]
	v_lshl_add_u64 v[46:47], v[0:1], 1, s[6:7]
	s_cmpk_lt_i32 s4, 0x2000
	s_cbranch_scc0 .LBB0_1526
.LBB0_1525:
	v_add_u32_e32 v53, s4, v52
	v_ashrrev_i32_e32 v54, 6, v53
	v_ashrrev_i32_e32 v55, 31, v54
	v_lshlrev_b64 v[0:1], 13, v[54:55]
	v_lshl_add_u64 v[48:49], v[44:45], 0, v[0:1]
	v_add_co_u32_e32 v4, vcc, 0x100000, v48
	global_load_dwordx4 v[0:3], v[48:49], off
	s_nop 0
	v_addc_co_u32_e32 v5, vcc, 0, v49, vcc
	v_add_co_u32_e32 v8, vcc, 0x200000, v48
	global_load_dwordx4 v[4:7], v[4:5], off
	s_nop 0
	v_addc_co_u32_e32 v9, vcc, 0, v49, vcc
	v_add_co_u32_e32 v12, vcc, 0x300000, v48
	global_load_dwordx4 v[8:11], v[8:9], off
	s_nop 0
	v_addc_co_u32_e32 v13, vcc, 0, v49, vcc
	v_add_co_u32_e32 v16, vcc, 0x400000, v48
	global_load_dwordx4 v[12:15], v[12:13], off
	s_nop 0
	v_addc_co_u32_e32 v17, vcc, 0, v49, vcc
	v_add_co_u32_e32 v20, vcc, 0x500000, v48
	global_load_dwordx4 v[16:19], v[16:17], off
	s_nop 0
	v_addc_co_u32_e32 v21, vcc, 0, v49, vcc
	v_add_co_u32_e32 v24, vcc, 0x600000, v48
	global_load_dwordx4 v[20:23], v[20:21], off
	s_nop 0
	v_addc_co_u32_e32 v25, vcc, 0, v49, vcc
	v_add_co_u32_e32 v28, vcc, 0x700000, v48
	global_load_dwordx4 v[24:27], v[24:25], off
	s_nop 0
	v_addc_co_u32_e32 v29, vcc, 0, v49, vcc
	v_add_co_u32_e32 v32, vcc, 0x800000, v48
	global_load_dwordx4 v[28:31], v[28:29], off
	s_nop 0
	v_addc_co_u32_e32 v33, vcc, 0, v49, vcc
	v_add_co_u32_e32 v36, vcc, 0x900000, v48
	global_load_dwordx4 v[32:35], v[32:33], off
	s_nop 0
	v_addc_co_u32_e32 v37, vcc, 0, v49, vcc
	v_add_co_u32_e32 v40, vcc, 0xa00000, v48
	global_load_dwordx4 v[36:39], v[36:37], off
	s_nop 0
	v_addc_co_u32_e32 v41, vcc, 0, v49, vcc
	v_add_co_u32_e32 v48, vcc, 0xb00000, v48
	global_load_dwordx4 v[40:43], v[40:41], off
	s_nop 0
	v_addc_co_u32_e32 v49, vcc, 0, v49, vcc
	global_load_dwordx4 v[48:51], v[48:49], off
	s_brev_b32 s8, 64
	s_addk_i32 s4, 0x400
	s_cmpk_eq_i32 s4, 0x2000
	s_waitcnt vmcnt(11)
	v_pk_add_f32 v[2:3], v[2:3], 0 op_sel_hi:[1,0]
	v_pk_add_f32 v[0:1], v[0:1], 0 op_sel_hi:[1,0]
	s_waitcnt vmcnt(10)
	v_pk_add_f32 v[2:3], v[2:3], v[6:7]
	v_pk_add_f32 v[0:1], v[0:1], v[4:5]
	s_waitcnt vmcnt(9)
	v_pk_add_f32 v[2:3], v[2:3], v[10:11]
	v_pk_add_f32 v[0:1], v[0:1], v[8:9]
	s_waitcnt vmcnt(8)
	v_pk_add_f32 v[2:3], v[2:3], v[14:15]
	v_pk_add_f32 v[0:1], v[0:1], v[12:13]
	s_waitcnt vmcnt(7)
	v_pk_add_f32 v[2:3], v[2:3], v[18:19]
	v_pk_add_f32 v[0:1], v[0:1], v[16:17]
	s_waitcnt vmcnt(6)
	v_pk_add_f32 v[2:3], v[2:3], v[22:23]
	v_pk_add_f32 v[0:1], v[0:1], v[20:21]
	s_waitcnt vmcnt(5)
	v_pk_add_f32 v[2:3], v[2:3], v[26:27]
	v_pk_add_f32 v[0:1], v[0:1], v[24:25]
	s_waitcnt vmcnt(4)
	v_pk_add_f32 v[2:3], v[2:3], v[30:31]
	v_pk_add_f32 v[0:1], v[0:1], v[28:29]
	s_waitcnt vmcnt(3)
	v_pk_add_f32 v[2:3], v[2:3], v[34:35]
	v_pk_add_f32 v[0:1], v[0:1], v[32:33]
	s_waitcnt vmcnt(2)
	v_pk_add_f32 v[2:3], v[2:3], v[38:39]
	v_pk_add_f32 v[0:1], v[0:1], v[36:37]
	s_waitcnt vmcnt(1)
	v_pk_add_f32 v[2:3], v[2:3], v[42:43]
	v_pk_add_f32 v[0:1], v[0:1], v[40:41]
	s_waitcnt vmcnt(0)
	v_pk_add_f32 v[2:3], v[2:3], v[50:51]
	v_pk_add_f32 v[0:1], v[0:1], v[48:49]
	s_nop 0
	s_nop 1
	v_cvt_pk_bf16_f32 v0, v0, v1
	s_nop 1
	v_cvt_pk_bf16_f32 v1, v2, v3
	v_lshlrev_b64 v[2:3], 12, v[54:55]
	v_lshl_add_u64 v[2:3], v[46:47], 0, v[2:3]
	v_add_co_u32_e32 v2, vcc, s8, v2
	s_mov_b32 s8, 0x100000
	s_nop 0
	v_addc_co_u32_e32 v3, vcc, 0, v3, vcc
	global_store_dwordx2 v[2:3], v[0:1], off
	s_addk_i32 s4, 0x1400
	s_cmpk_lt_i32 s4, 0x2000
	s_cbranch_scc1 .LBB0_1525
	s_branch .LBB0_1526
	v_add_u32_e32 v0, 0x200, v53
	v_ashrrev_i32_e32 v48, 6, v0
	v_ashrrev_i32_e32 v49, 31, v48
	v_lshlrev_b64 v[0:1], 13, v[48:49]
	v_lshl_add_u64 v[50:51], v[44:45], 0, v[0:1]
	v_add_co_u32_e32 v4, vcc, s8, v50
	s_mov_b32 s8, 0x200000
	s_nop 0
	v_addc_co_u32_e32 v5, vcc, 0, v51, vcc
	v_add_co_u32_e32 v8, vcc, s8, v50
	s_mov_b32 s8, 0x300000
	s_nop 0
	v_addc_co_u32_e32 v9, vcc, 0, v51, vcc
	v_add_co_u32_e32 v12, vcc, s8, v50
	s_mov_b32 s8, 0x400000
	s_nop 0
	v_addc_co_u32_e32 v13, vcc, 0, v51, vcc
	v_add_co_u32_e32 v16, vcc, s8, v50
	s_mov_b32 s8, 0x500000
	s_nop 0
	v_addc_co_u32_e32 v17, vcc, 0, v51, vcc
	v_add_co_u32_e32 v20, vcc, s8, v50
	s_mov_b32 s8, 0x600000
	s_nop 0
	v_addc_co_u32_e32 v21, vcc, 0, v51, vcc
	v_add_co_u32_e32 v24, vcc, s8, v50
	global_load_dwordx4 v[0:3], v[50:51], off
	s_nop 0
	v_addc_co_u32_e32 v25, vcc, 0, v51, vcc
	s_mov_b32 s8, 0x700000
	global_load_dwordx4 v[4:7], v[4:5], off
	v_add_co_u32_e32 v28, vcc, s8, v50
	global_load_dwordx4 v[8:11], v[8:9], off
	s_nop 0
	v_addc_co_u32_e32 v29, vcc, 0, v51, vcc
	s_mov_b32 s8, 0x800000
	global_load_dwordx4 v[12:15], v[12:13], off
	v_add_co_u32_e32 v32, vcc, s8, v50
	global_load_dwordx4 v[16:19], v[16:17], off
	s_nop 0
	v_addc_co_u32_e32 v33, vcc, 0, v51, vcc
	s_mov_b32 s8, 0x900000
	global_load_dwordx4 v[20:23], v[20:21], off
	v_add_co_u32_e32 v36, vcc, s8, v50
	global_load_dwordx4 v[24:27], v[24:25], off
	s_nop 0
	v_addc_co_u32_e32 v37, vcc, 0, v51, vcc
	s_mov_b32 s8, 0xa00000
	global_load_dwordx4 v[28:31], v[28:29], off
	v_add_co_u32_e32 v40, vcc, s8, v50
	global_load_dwordx4 v[32:35], v[32:33], off
	s_nop 0
	v_addc_co_u32_e32 v41, vcc, 0, v51, vcc
	s_mov_b32 s8, 0xb00000
	global_load_dwordx4 v[36:39], v[36:37], off
	v_add_co_u32_e32 v50, vcc, s8, v50
	global_load_dwordx4 v[40:43], v[40:41], off
	s_nop 0
	v_addc_co_u32_e32 v51, vcc, 0, v51, vcc
	global_load_dwordx4 v[54:57], v[50:51], off
	s_waitcnt vmcnt(11)
	v_pk_add_f32 v[2:3], v[2:3], 0 op_sel_hi:[1,0]
	v_pk_add_f32 v[0:1], v[0:1], 0 op_sel_hi:[1,0]
	s_waitcnt vmcnt(10)
	v_pk_add_f32 v[2:3], v[2:3], v[6:7]
	v_pk_add_f32 v[0:1], v[0:1], v[4:5]
	s_waitcnt vmcnt(9)
	v_pk_add_f32 v[2:3], v[2:3], v[10:11]
	v_pk_add_f32 v[0:1], v[0:1], v[8:9]
	s_waitcnt vmcnt(8)
	v_pk_add_f32 v[2:3], v[2:3], v[14:15]
	v_pk_add_f32 v[0:1], v[0:1], v[12:13]
	s_waitcnt vmcnt(7)
	v_pk_add_f32 v[2:3], v[2:3], v[18:19]
	v_pk_add_f32 v[0:1], v[0:1], v[16:17]
	s_waitcnt vmcnt(6)
	v_pk_add_f32 v[2:3], v[2:3], v[22:23]
	v_pk_add_f32 v[0:1], v[0:1], v[20:21]
	s_waitcnt vmcnt(5)
	v_pk_add_f32 v[2:3], v[2:3], v[26:27]
	v_pk_add_f32 v[0:1], v[0:1], v[24:25]
	s_waitcnt vmcnt(4)
	v_pk_add_f32 v[2:3], v[2:3], v[30:31]
	v_pk_add_f32 v[0:1], v[0:1], v[28:29]
	s_waitcnt vmcnt(3)
	v_pk_add_f32 v[2:3], v[2:3], v[34:35]
	v_pk_add_f32 v[0:1], v[0:1], v[32:33]
	s_waitcnt vmcnt(2)
	v_pk_add_f32 v[2:3], v[2:3], v[38:39]
	v_pk_add_f32 v[0:1], v[0:1], v[36:37]
	s_waitcnt vmcnt(1)
	v_pk_add_f32 v[2:3], v[2:3], v[42:43]
	v_pk_add_f32 v[0:1], v[0:1], v[40:41]
	s_waitcnt vmcnt(0)
	v_pk_add_f32 v[2:3], v[2:3], v[56:57]
	v_pk_add_f32 v[0:1], v[0:1], v[54:55]
	s_nop 0
	s_nop 1
	v_cvt_pk_bf16_f32 v0, v0, v1
	s_nop 1
	v_cvt_pk_bf16_f32 v1, v2, v3
	v_lshlrev_b64 v[2:3], 12, v[48:49]
	v_lshl_add_u64 v[2:3], v[46:47], 0, v[2:3]
	v_add_co_u32_e32 v2, vcc, 0x2000000, v2
	s_nop 1
	v_addc_co_u32_e32 v3, vcc, 0, v3, vcc
	global_store_dwordx2 v[2:3], v[0:1], off
	s_cbranch_scc0 .LBB0_1525

.LBB0_1749:
	s_lshl_b64 s[4:5], s[6:7], 20
	s_add_u32 s4, s14, s4
	s_addc_u32 s5, s15, s5
	v_lshl_add_u64 v[64:65], s[4:5], 0, v[140:141]
	v_lshlrev_b64 v[66:67], 2, v[152:153]
	v_lshl_add_u64 v[64:65], v[64:65], 0, v[66:67]
	global_store_dwordx4 v[64:65], v[60:63], off
	global_store_dwordx4 v[64:65], v[56:59], off offset:16
	global_store_dwordx4 v[64:65], v[36:39], off offset:512
	global_store_dwordx4 v[64:65], v[32:35], off offset:528
	s_nop 1
	v_lshl_add_u64 v[32:33], s[4:5], 0, v[142:143]
	v_lshl_add_u64 v[32:33], v[32:33], 0, v[66:67]
	global_store_dwordx4 v[32:33], v[52:55], off
	global_store_dwordx4 v[32:33], v[48:51], off offset:16
	global_store_dwordx4 v[32:33], v[20:23], off offset:512
	global_store_dwordx4 v[32:33], v[16:19], off offset:528
	s_nop 1
	v_lshl_add_u64 v[16:17], s[4:5], 0, v[144:145]
	v_lshl_add_u64 v[16:17], v[16:17], 0, v[66:67]
	global_store_dwordx4 v[16:17], v[44:47], off
	global_store_dwordx4 v[16:17], v[40:43], off offset:16
	global_store_dwordx4 v[16:17], v[12:15], off offset:512
	global_store_dwordx4 v[16:17], v[8:11], off offset:528
	s_nop 1
	v_lshl_add_u64 v[8:9], s[4:5], 0, v[146:147]
	v_lshl_add_u64 v[8:9], v[8:9], 0, v[66:67]
	global_store_dwordx4 v[8:9], v[28:31], off
	global_store_dwordx4 v[8:9], v[24:27], off offset:16
	global_store_dwordx4 v[8:9], v[4:7], off offset:512
	global_store_dwordx4 v[8:9], v[0:3], off offset:528
	s_waitcnt vmcnt(0)
	s_waitcnt vmcnt(0)
	s_barrier
	s_and_saveexec_b64 s[4:5], s[18:19]
	s_cbranch_execz .LBB0_1751
	s_lshl_b32 s8, s0, 6
	s_ashr_i32 s9, s8, 31
	s_lshl_b64 s[8:9], s[8:9], 2
	s_add_u32 s8, s57, s8
	s_addc_u32 s9, s58, s9
	buffer_wbl2 sc1
	s_waitcnt vmcnt(0)
	v_mov_b64_e32 v[0:1], s[8:9]
	flat_atomic_add v0, v[0:1], v158 sc0
	s_waitcnt vmcnt(0) lgkmcnt(0)
	ds_write_b32 v137, v0
	v_mov_b64_e32 v[2:3], s[8:9]

.Lsl_go_out5:
.LBB0_1751:
	s_or_b64 exec, exec, s[4:5]
	s_waitcnt lgkmcnt(0)
	s_barrier
	ds_read_b32 v0, v137
	s_waitcnt lgkmcnt(0)
	v_readfirstlane_b32 s6, v0
	v_mov_b32_e32 v8, v183
	buffer_inv sc1
	s_waitcnt vmcnt(0)
	s_lshl_b32 s0, s0, 2
	v_lshlrev_b32_e32 v0, 2, v8
	v_and_b32_e32 v0, 0xfc, v0
	v_or_b32_e32 v4, s1, v0
	s_ashr_i32 s1, s0, 31
	s_lshl_b64 s[0:1], s[0:1], 2
	v_and_b32_e32 v2, 63, v8
	s_add_u32 s0, s16, s0
	v_ashrrev_i32_e32 v5, 31, v4
	s_addc_u32 s1, s17, s1
	v_lshlrev_b32_e32 v136, 2, v2
	v_cmp_gt_u32_e32 vcc, 4, v2
	s_lshl_b32 s6, s6, 9
	v_cmp_eq_u32_e64 s[4:5], 0, v2
	v_lshl_add_u64 v[0:1], v[4:5], 2, s[14:15]
	v_lshl_add_u64 v[2:3], s[0:1], 0, v[136:137]
	v_lshl_add_u64 v[4:5], v[4:5], 1, s[12:13]
	s_cmpk_lt_i32 s6, 0x2000
	s_cbranch_scc1 .LBB0_1754
	s_branch .LBB0_1762

.LBB0_1756:
	s_or_b64 exec, exec, s[0:1]
	s_addk_i32 s6, 0x1000
	s_cmpk_lt_i32 s6, 0x2000
	s_cbranch_scc1 .LBB0_1754
	s_branch .LBB0_1762
	v_add_u32_e32 v6, 0x200, v9
	v_ashrrev_i32_e32 v16, 6, v6
	s_waitcnt lgkmcnt(0)
	v_ashrrev_i32_e32 v17, 31, v16
	v_add_u32_e32 v6, 0x2000, v16
	v_lshlrev_b64 v[16:17], 13, v[16:17]
	v_lshl_add_u64 v[44:45], v[0:1], 0, v[16:17]
	v_add_co_u32_e64 v20, s[0:1], s67, v44
	v_ashrrev_i32_e32 v7, 31, v6
	s_nop 0
	v_addc_co_u32_e64 v21, s[0:1], 0, v45, s[0:1]
	v_add_co_u32_e64 v24, s[0:1], s72, v44
	v_lshlrev_b64 v[18:19], 12, v[6:7]
	s_nop 0
	v_addc_co_u32_e64 v25, s[0:1], 0, v45, s[0:1]
	v_add_co_u32_e64 v28, s[0:1], s73, v44
	v_lshl_add_u64 v[48:49], v[4:5], 0, v[18:19]
	s_nop 0
	v_addc_co_u32_e64 v29, s[0:1], 0, v45, s[0:1]
	v_add_co_u32_e64 v32, s[0:1], s74, v44
	global_load_dwordx2 v[50:51], v[48:49], off
	global_load_dwordx4 v[16:19], v[44:45], off
	v_addc_co_u32_e64 v33, s[0:1], 0, v45, s[0:1]
	v_add_co_u32_e64 v36, s[0:1], s75, v44
	global_load_dwordx4 v[20:23], v[20:21], off
	s_nop 0
	global_load_dwordx4 v[24:27], v[24:25], off
	v_addc_co_u32_e64 v37, s[0:1], 0, v45, s[0:1]
	v_add_co_u32_e64 v40, s[0:1], s76, v44
	global_load_dwordx4 v[28:31], v[28:29], off
	s_nop 0
	global_load_dwordx4 v[32:35], v[32:33], off
	v_addc_co_u32_e64 v41, s[0:1], 0, v45, s[0:1]
	v_add_co_u32_e64 v44, s[0:1], s77, v44
	global_load_dwordx4 v[36:39], v[36:37], off
	s_nop 0
	global_load_dwordx4 v[40:43], v[40:41], off
	v_addc_co_u32_e64 v45, s[0:1], 0, v45, s[0:1]
	global_load_dwordx4 v[44:47], v[44:45], off
	s_waitcnt vmcnt(0)
	v_lshlrev_b32_e32 v52, 16, v50
	v_and_b32_e32 v53, 0xffff0000, v50
	v_lshlrev_b32_e32 v50, 16, v51
	v_and_b32_e32 v51, 0xffff0000, v51
	v_pk_add_f32 v[18:19], v[18:19], v[50:51]
	v_pk_add_f32 v[16:17], v[16:17], v[52:53]
	v_pk_add_f32 v[18:19], v[22:23], v[18:19]
	v_pk_add_f32 v[16:17], v[20:21], v[16:17]
	v_pk_add_f32 v[18:19], v[26:27], v[18:19]
	v_pk_add_f32 v[16:17], v[24:25], v[16:17]
	v_pk_add_f32 v[18:19], v[30:31], v[18:19]
	v_pk_add_f32 v[16:17], v[28:29], v[16:17]
	v_pk_add_f32 v[18:19], v[34:35], v[18:19]
	v_pk_add_f32 v[16:17], v[32:33], v[16:17]
	v_pk_add_f32 v[18:19], v[38:39], v[18:19]
	v_pk_add_f32 v[16:17], v[36:37], v[16:17]
	v_pk_add_f32 v[18:19], v[42:43], v[18:19]
	v_pk_add_f32 v[16:17], v[40:41], v[16:17]
	v_pk_add_f32 v[18:19], v[46:47], v[18:19]
	v_pk_add_f32 v[20:21], v[44:45], v[16:17]
	v_mul_f32_e32 v17, v19, v19
	v_mul_f32_e32 v16, v21, v21
	v_fmac_f32_e32 v16, v20, v20
	v_fmac_f32_e32 v17, v18, v18
	v_add_f32_e32 v16, v16, v17
	ds_bpermute_b32 v17, v10, v16
	s_nop 1
	v_cvt_pk_bf16_f32 v20, v20, v21
	s_nop 1
	v_cvt_pk_bf16_f32 v21, v18, v19
	global_store_dwordx2 v[48:49], v[20:21], off
	s_waitcnt lgkmcnt(0)
	v_add_f32_e32 v16, v16, v17
	ds_bpermute_b32 v17, v11, v16
	s_waitcnt lgkmcnt(0)
	v_add_f32_e32 v16, v16, v17
	ds_bpermute_b32 v17, v12, v16
	s_waitcnt lgkmcnt(0)
	v_add_f32_e32 v16, v16, v17
	ds_bpermute_b32 v17, v13, v16
	s_waitcnt lgkmcnt(0)
	v_add_f32_e32 v16, v16, v17
	ds_bpermute_b32 v17, v14, v16
	s_waitcnt lgkmcnt(0)
	v_add_f32_e32 v16, v16, v17
	ds_bpermute_b32 v17, v15, v16
	s_and_saveexec_b64 s[0:1], vcc
	s_cbranch_execz .LBB0_1758
	s_waitcnt lgkmcnt(0)
	v_add_f32_e32 v16, v16, v17
	v_lshlrev_b64 v[6:7], 7, v[6:7]
	v_cndmask_b32_e64 v16, 0, v16, s[4:5]
	v_lshl_add_u64 v[6:7], v[2:3], 0, v[6:7]
	flat_store_dword v[6:7], v16 sc1

.LBB0_1762:
	s_waitcnt vmcnt(0)
	s_waitcnt lgkmcnt(0)
	s_barrier
	s_and_saveexec_b64 s[0:1], s[18:19]
	s_cbranch_execz .LBB0_1764
	v_mov_b64_e32 v[0:1], s[34:35]
	flat_atomic_add v0, v[0:1], v158 sc0
	s_waitcnt vmcnt(0) lgkmcnt(0)
	v_cmp_eq_u32_e32 vcc, 63, v0
	s_nop 1
	v_cndmask_b32_e64 v0, 0, 1, vcc
	ds_write_b32 v137, v0
